# lgkmcnt ladders at band-loop head and last attention step collapsed as well
# speedup vs baseline: 1.0048x; 1.0048x over previous
.LBB0_285:
	s_waitcnt lgkmcnt(0)
	v_mfma_f32_32x32x16_bf16 v[144:159], v[220:223], v[184:187], v[80:95]
	v_add_f32_e32 v2, v112, v113
	v_add_f32_e32 v2, v114, v2
	v_add_f32_e32 v2, v115, v2
	s_lshl_b32 s2, s96, 1
	v_add_f32_e32 v2, v116, v2
	v_add_u32_e32 v0, s2, v233
	v_add_f32_e32 v2, v117, v2
	v_cvt_pk_bf16_f32 v188, v112, v113
	v_cvt_pk_bf16_f32 v189, v114, v115
	v_mfma_f32_32x32x16_bf16 v[128:143], v[216:219], v[184:187], v[80:95]
	v_add_f32_e32 v2, v118, v2
	v_add_f32_e32 v2, v119, v2
	v_add_f32_e32 v2, v120, v2
	v_add_f32_e32 v2, v121, v2
	v_cvt_pk_bf16_f32 v190, v116, v117
	v_cvt_pk_bf16_f32 v191, v118, v119
	v_mfma_f32_32x32x16_bf16 v[144:159], v[212:215], v[176:179], v[144:159]
	v_add_f32_e32 v2, v122, v2
	v_add_f32_e32 v2, v123, v2
	v_add_f32_e32 v2, v124, v2
	v_add_f32_e32 v2, v125, v2
	v_cvt_pk_bf16_f32 v180, v120, v121
	v_cvt_pk_bf16_f32 v181, v122, v123
	v_mfma_f32_32x32x16_bf16 v[128:143], v[208:211], v[176:179], v[128:143]
	v_add_f32_e32 v2, v126, v2
	v_add_f32_e32 v2, v127, v2
	v_add_f32_e32 v2, v96, v2
	v_add_f32_e32 v2, v97, v2
	v_cvt_pk_bf16_f32 v182, v124, v125
	v_cvt_pk_bf16_f32 v183, v126, v127
	v_mfma_f32_32x32x16_bf16 v[144:159], v[204:207], v[172:175], v[144:159]
	v_add_f32_e32 v2, v98, v2
	v_add_f32_e32 v2, v99, v2
	v_add_f32_e32 v2, v100, v2
	v_add_f32_e32 v2, v101, v2
	v_cvt_pk_bf16_f32 v168, v96, v97
	v_cvt_pk_bf16_f32 v169, v98, v99
	v_mfma_f32_32x32x16_bf16 v[128:143], v[200:203], v[172:175], v[128:143]
	v_add_f32_e32 v2, v102, v2
	v_add_f32_e32 v2, v103, v2
	v_add_f32_e32 v2, v104, v2
	v_add_f32_e32 v2, v105, v2
	v_cvt_pk_bf16_f32 v170, v100, v101
	v_cvt_pk_bf16_f32 v171, v102, v103
	v_mfma_f32_32x32x16_bf16 v[144:159], v[196:199], v[164:167], v[144:159]
	v_add_f32_e32 v2, v106, v2
	v_add_f32_e32 v2, v107, v2
	v_add_f32_e32 v2, v108, v2
	v_add_f32_e32 v2, v109, v2
	v_cvt_pk_bf16_f32 v160, v104, v105
	v_cvt_pk_bf16_f32 v161, v106, v107
	v_mfma_f32_32x32x16_bf16 v[128:143], v[192:195], v[164:167], v[128:143]
	v_add_f32_e32 v2, v110, v2
	v_add_f32_e32 v100, v111, v2
	v_cvt_pk_bf16_f32 v162, v108, v109
	v_cvt_pk_bf16_f32 v163, v110, v111
	ds_read_b64_tr_b16 v[96:97], v0 offset:24576
	ds_read_b64_tr_b16 v[98:99], v0 offset:25088
	ds_read_b64_tr_b16 v[10:11], v0 offset:28672
	ds_read_b64_tr_b16 v[12:13], v0 offset:29184
	ds_read_b64_tr_b16 v[6:7], v0 offset:32768
	ds_read_b64_tr_b16 v[8:9], v0 offset:33280
	ds_read_b64_tr_b16 v[2:3], v0 offset:36864
	ds_read_b64_tr_b16 v[4:5], v0 offset:37376
	s_add_i32 s2, s12, 1
	s_cmp_ge_u32 s2, s68
	s_cselect_b64 s[92:93], -1, 0
	s_and_b64 vcc, exec, s[92:93]
	v_lshl_add_u64 v[242:243], v[238:239], 0, s[94:95]
	s_cbranch_vccnz .LBB0_287
	v_lshl_add_u64 v[102:103], v[242:243], 0, s[72:73]
	s_add_i32 s2, s24, s22
	s_mov_b32 m0, s2
	s_nop 0
	global_load_lds_dwordx4 v[102:103], off

; __device__ __forceinline__ void cmask(f32x16&p0,f32x16&p1,int jb,int qrel,int hi){
;   const float NEG=-INFINITY; (void)hi;
;   #pragma unroll
;   for(int r=0;r<16;++r){ if(jb>(qrel>>6)){p0[r]=NEG; p1[r]=NEG;} }
; }
.LBB0_335:
	v_add_f32_e32 v0, v112, v113
	v_add_f32_e32 v0, v114, v0
	v_add_f32_e32 v0, v115, v0
	v_add_f32_e32 v0, v116, v0
	v_add_u32_e32 v14, s4, v233
	v_add_f32_e32 v0, v117, v0
	v_cvt_pk_bf16_f32 v188, v112, v113
	v_cvt_pk_bf16_f32 v189, v114, v115
	s_waitcnt lgkmcnt(0)
	v_mfma_f32_32x32x16_bf16 v[128:143], v[220:223], v[184:187], v[80:95]
	v_mfma_f32_32x32x16_bf16 v[80:95], v[216:219], v[184:187], v[80:95]
	v_add_f32_e32 v0, v118, v0
	v_add_f32_e32 v0, v119, v0
	v_add_f32_e32 v0, v120, v0
	v_add_f32_e32 v0, v121, v0
	v_cvt_pk_bf16_f32 v190, v116, v117
	v_cvt_pk_bf16_f32 v191, v118, v119
	s_nop 0
	v_add_f32_e32 v0, v122, v0
	v_add_f32_e32 v0, v123, v0
	v_add_f32_e32 v0, v124, v0
	v_add_f32_e32 v0, v125, v0
	v_cvt_pk_bf16_f32 v180, v120, v121
	v_cvt_pk_bf16_f32 v181, v122, v123
	v_mfma_f32_32x32x16_bf16 v[128:143], v[212:215], v[176:179], v[128:143]
	v_mfma_f32_32x32x16_bf16 v[80:95], v[208:211], v[176:179], v[80:95]
	v_add_f32_e32 v0, v126, v0
	v_add_f32_e32 v0, v127, v0
	v_add_f32_e32 v0, v96, v0
	v_add_f32_e32 v0, v97, v0
	v_cvt_pk_bf16_f32 v182, v124, v125
	v_cvt_pk_bf16_f32 v183, v126, v127
	s_nop 0
	v_add_f32_e32 v0, v98, v0
	v_add_f32_e32 v0, v99, v0
	v_add_f32_e32 v0, v100, v0
	v_add_f32_e32 v0, v101, v0
	v_cvt_pk_bf16_f32 v168, v96, v97
	v_cvt_pk_bf16_f32 v169, v98, v99
	v_mfma_f32_32x32x16_bf16 v[128:143], v[204:207], v[172:175], v[128:143]
	v_mfma_f32_32x32x16_bf16 v[80:95], v[200:203], v[172:175], v[80:95]
	v_add_f32_e32 v0, v102, v0
	v_add_f32_e32 v0, v103, v0
	v_add_f32_e32 v0, v104, v0
	v_add_f32_e32 v0, v105, v0
	v_cvt_pk_bf16_f32 v170, v100, v101
	v_cvt_pk_bf16_f32 v171, v102, v103
	s_nop 0
	v_add_f32_e32 v0, v106, v0
	v_add_f32_e32 v0, v107, v0
	v_add_f32_e32 v0, v108, v0
	v_add_f32_e32 v0, v109, v0
	v_cvt_pk_bf16_f32 v160, v104, v105
	v_cvt_pk_bf16_f32 v161, v106, v107
	v_mfma_f32_32x32x16_bf16 v[128:143], v[196:199], v[164:167], v[128:143]
	v_mfma_f32_32x32x16_bf16 v[80:95], v[192:195], v[164:167], v[80:95]
	v_add_f32_e32 v0, v110, v0
	v_add_f32_e32 v0, v111, v0
	v_cvt_pk_bf16_f32 v162, v108, v109
	v_cvt_pk_bf16_f32 v163, v110, v111
	ds_read_b64_tr_b16 v[144:145], v14 offset:24576
	ds_read_b64_tr_b16 v[146:147], v14 offset:25088
	ds_read_b64_tr_b16 v[10:11], v14 offset:28672
	ds_read_b64_tr_b16 v[12:13], v14 offset:29184
	ds_read_b64_tr_b16 v[6:7], v14 offset:32768
	ds_read_b64_tr_b16 v[8:9], v14 offset:33280
	ds_read_b64_tr_b16 v[2:3], v14 offset:36864
	ds_read_b64_tr_b16 v[4:5], v14 offset:37376
	s_cmpk_lt_i32 s33, 0x180
	s_cselect_b64 vcc, -1, 0
	v_cndmask_b32_e32 v97, v129, v248, vcc
	v_cndmask_b32_e32 v96, v128, v248, vcc
	v_max_f32_e32 v15, v97, v97
	v_max_f32_e32 v112, v96, v96
	v_cndmask_b32_e32 v99, v131, v248, vcc
	v_cndmask_b32_e32 v98, v130, v248, vcc
	v_cndmask_b32_e32 v82, v82, v248, vcc
	v_cndmask_b32_e32 v81, v81, v248, vcc
	v_cndmask_b32_e32 v80, v80, v248, vcc
	v_max_f32_e32 v15, v112, v15
	v_cndmask_b32_e32 v103, v135, v248, vcc
	v_cndmask_b32_e32 v102, v134, v248, vcc
	v_cndmask_b32_e32 v100, v132, v248, vcc
	v_cndmask_b32_e32 v83, v83, v248, vcc
	v_max3_f32 v112, v98, v99, v81
	v_max3_f32 v15, v15, v80, v82
	v_cndmask_b32_e32 v101, v133, v248, vcc
	v_cndmask_b32_e32 v87, v87, v248, vcc
	v_cndmask_b32_e32 v86, v86, v248, vcc
	v_cndmask_b32_e32 v84, v84, v248, vcc
	v_max3_f32 v15, v15, v83, v100
	v_max3_f32 v112, v112, v102, v103
	v_cndmask_b32_e32 v107, v139, v248, vcc
	v_cndmask_b32_e32 v106, v138, v248, vcc
	v_cndmask_b32_e32 v104, v136, v248, vcc
	v_cndmask_b32_e32 v85, v85, v248, vcc
	v_max3_f32 v15, v15, v101, v84
	v_max3_f32 v112, v112, v86, v87
	v_cndmask_b32_e32 v105, v137, v248, vcc
	v_cndmask_b32_e32 v91, v91, v248, vcc
	v_cndmask_b32_e32 v90, v90, v248, vcc
	v_cndmask_b32_e32 v88, v88, v248, vcc
	v_max3_f32 v15, v15, v85, v104
	v_max3_f32 v112, v112, v106, v107
	v_cndmask_b32_e32 v111, v143, v248, vcc
	v_cndmask_b32_e32 v110, v142, v248, vcc
	v_cndmask_b32_e32 v108, v140, v248, vcc
	v_cndmask_b32_e32 v89, v89, v248, vcc
	v_max3_f32 v15, v15, v105, v88
	v_max3_f32 v112, v112, v90, v91
	v_cndmask_b32_e32 v109, v141, v248, vcc
	v_cndmask_b32_e32 v95, v95, v248, vcc
	v_cndmask_b32_e32 v94, v94, v248, vcc
	v_cndmask_b32_e32 v92, v92, v248, vcc
	v_max3_f32 v15, v15, v89, v108
	v_max3_f32 v112, v112, v110, v111
	v_cndmask_b32_e32 v93, v93, v248, vcc
	v_max3_f32 v15, v15, v109, v92
	v_max3_f32 v112, v112, v94, v95
	v_max3_f32 v15, v15, v93, v112
	v_mov_b32_e32 v112, v15
	s_nop 1
	v_permlane32_swap_b32_e32 v15, v112
	v_max_f32_e32 v15, v15, v112
	v_cmp_lt_f32_e32 vcc, s11, v15
	s_cmp_lg_u64 vcc, 0
	v_add_f32_e32 v0, v235, v0
	s_cselect_b64 s[38:39], -1, 0
	s_cbranch_vccnz .LBB0_340
